# attention B unit prologue: the rendezvous behind the bias-table build removed (the first tile iteration's barrier covers it)
# speedup vs baseline: 1.0076x; 1.0015x over previous
.LBB0_380:
	s_and_b32 s30, s28, 7
	s_mul_i32 s4, s30, 0x201
	s_mov_b64 s[12:13], 0
	v_mov_b32_e32 v0, v111
	v_mov_b32_e32 v1, v110
	v_mov_b32_e32 v2, v215
	s_barrier
	v_mul_hi_u32 v3, v215, s21
	v_lshrrev_b32_e32 v3, 9, v3
	v_mad_u32_u24 v22, v3, 48, v111
	v_sub_u32_e32 v4, v110, v3
	v_mad_u32_u24 v4, v3, s22, v4
	v_med3_i32 v4, v4, s23, v114
	v_add_u32_e32 v4, s4, v4
	v_ashrrev_i32_e32 v5, 31, v4
	v_lshl_add_u64 v[4:5], v[4:5], 2, s[66:67]
	global_load_dword v16, v[4:5], off offset:1024
	v_add_u32_e32 v2, 0x200, v215
	v_mul_hi_u32 v3, v2, s21
	v_lshrrev_b32_e32 v3, 9, v3
	v_mad_u32_u24 v23, v3, 48, v111
	v_sub_u32_e32 v6, v110, v3
	v_add_u32_e32 v6, 0xfffffe00, v6
	v_mad_u32_u24 v6, v3, s22, v6
	v_med3_i32 v6, v6, s23, v114
	v_add_u32_e32 v6, s4, v6
	v_ashrrev_i32_e32 v7, 31, v6
	v_lshl_add_u64 v[6:7], v[6:7], 2, s[66:67]
	global_load_dword v17, v[6:7], off offset:1024
	v_add_u32_e32 v2, 0x400, v215
	v_mul_hi_u32 v3, v2, s21
	v_lshrrev_b32_e32 v3, 9, v3
	v_mad_u32_u24 v24, v3, 48, v111
	v_sub_u32_e32 v8, v110, v3
	v_add_u32_e32 v8, 0xfffffc00, v8
	v_mad_u32_u24 v8, v3, s22, v8
	v_med3_i32 v8, v8, s23, v114
	v_add_u32_e32 v8, s4, v8
	v_ashrrev_i32_e32 v9, 31, v8
	v_lshl_add_u64 v[8:9], v[8:9], 2, s[66:67]
	global_load_dword v18, v[8:9], off offset:1024
	v_add_u32_e32 v2, 0x600, v215
	v_mul_hi_u32 v3, v2, s21
	v_lshrrev_b32_e32 v3, 9, v3
	v_mad_u32_u24 v25, v3, 48, v111
	v_sub_u32_e32 v10, v110, v3
	v_add_u32_e32 v10, 0xfffffa00, v10
	v_mad_u32_u24 v10, v3, s22, v10
	v_med3_i32 v10, v10, s23, v114
	v_add_u32_e32 v10, s4, v10
	v_ashrrev_i32_e32 v11, 31, v10
	v_lshl_add_u64 v[10:11], v[10:11], 2, s[66:67]
	global_load_dword v19, v[10:11], off offset:1024
	v_add_u32_e32 v2, 0x800, v215
	v_mul_hi_u32 v3, v2, s21
	v_lshrrev_b32_e32 v3, 9, v3
	v_mad_u32_u24 v26, v3, 48, v111
	v_sub_u32_e32 v12, v110, v3
	v_add_u32_e32 v12, 0xfffff800, v12
	v_mad_u32_u24 v12, v3, s22, v12
	v_med3_i32 v12, v12, s23, v114
	v_add_u32_e32 v12, s4, v12
	v_ashrrev_i32_e32 v13, 31, v12
	v_lshl_add_u64 v[12:13], v[12:13], 2, s[66:67]
	global_load_dword v20, v[12:13], off offset:1024
	v_cmp_gt_u32_e32 vcc, 16, v215
	s_and_saveexec_b64 s[12:13], vcc
	v_add_u32_e32 v2, 0xa00, v215
	v_mul_hi_u32 v3, v2, s21
	v_lshrrev_b32_e32 v3, 9, v3
	v_mad_u32_u24 v27, v3, 48, v111
	v_sub_u32_e32 v14, v110, v3
	v_add_u32_e32 v14, 0xfffff600, v14
	v_mad_u32_u24 v14, v3, s22, v14
	v_med3_i32 v14, v14, s23, v114
	v_add_u32_e32 v14, s4, v14
	v_ashrrev_i32_e32 v15, 31, v14
	v_lshl_add_u64 v[14:15], v[14:15], 2, s[66:67]
	global_load_dword v21, v[14:15], off offset:1024
	s_or_b64 exec, exec, s[12:13]
	s_ashr_i32 s13, s28, 7
	s_lshl_b32 s37, s13, 8
	s_lshl_b32 s4, s28, 8
	s_add_i32 s37, s37, s40
	s_lshl_b32 s12, s13, 2
	s_and_b32 s31, s4, 0x7800
	s_ashr_i32 s29, s37, 31
	s_add_u32 s4, s37, s31
	s_addc_u32 s29, s29, 0
	s_mul_i32 s34, s29, 0x1800
	s_mul_hi_u32 s35, s4, 0x1800
	s_add_i32 s35, s35, s34
	s_mul_i32 s34, s4, 0x1800
	s_add_u32 s34, s10, s34
	s_addc_u32 s35, s11, s35
	s_lshl_b32 s36, s30, 7
	s_add_u32 s34, s34, s36
	s_addc_u32 s35, s35, 0
	v_lshl_add_u64 v[0:1], s[34:35], 0, v[132:133]
	v_lshl_add_u64 v[0:1], v[0:1], 0, v[134:135]
	global_load_dwordx4 v[64:67], v[0:1], off offset:3072
	global_load_dwordx4 v[68:71], v[0:1], off offset:3104
	global_load_dwordx4 v[72:75], v[0:1], off offset:3136
	global_load_dwordx4 v[76:79], v[0:1], off offset:3168
	s_mulk_i32 s31, 0x1800
	s_add_u32 s31, s10, s31
	s_addc_u32 s35, s11, 0
	s_add_u32 s31, s31, s36
	s_addc_u32 s35, s35, 0
	s_add_u32 s43, s31, 0x1000
	s_addc_u32 s44, s35, 0
	v_readfirstlane_b32 s34, v215
	s_add_u32 s36, s31, 0x1400
	s_addc_u32 s38, s35, 0
	s_max_i32 s42, s12, 8
	s_lshr_b32 s39, s34, 6
	s_add_i32 s35, s42, -8
	v_lshl_or_b32 v0, s39, 3, v172
	s_add_i32 s31, s12, 4
	v_lshrrev_b32_e32 v2, 1, v0
	s_mul_i32 s54, s35, 0x60000
	s_mul_hi_u32 s45, s35, 0x60000
	v_xor_b32_e32 v2, v2, v215
	s_add_u32 s52, s43, s54
	v_lshlrev_b32_e32 v2, 3, v2
	s_addc_u32 s53, s44, s45
	s_lshl_b32 s34, s39, 10
	v_mul_lo_u32 v3, v0, s18
	v_and_b32_e32 v32, 56, v2
	s_add_i32 s34, s34, 0
	v_or_b32_e32 v98, v32, v3
	s_add_u32 s54, s36, s54
	v_mov_b32_e32 v1, v99
	v_or_b32_e32 v0, v115, v3
	v_lshl_add_u64 v[2:3], v[98:99], 1, s[52:53]
	s_addc_u32 s55, s38, s45
	s_mov_b32 m0, s34
	v_lshl_add_u64 v[4:5], v[0:1], 1, s[54:55]
	s_add_i32 s45, s42, -7
	global_load_lds_dwordx4 v[2:3], off
	s_add_i32 m0, s34, 0x2000
	s_nop 0
	global_load_lds_dwordx4 v[4:5], off
	s_waitcnt vmcnt(6)
	v_mul_f32_e32 v16, 0x3fb8aa3b, v16
	ds_write_b32 v22, v16
	v_mul_f32_e32 v17, 0x3fb8aa3b, v17
	ds_write_b32 v23, v17 offset:2048
	v_mul_f32_e32 v18, 0x3fb8aa3b, v18
	ds_write_b32 v24, v18 offset:4096
	v_mul_f32_e32 v19, 0x3fb8aa3b, v19
	ds_write_b32 v25, v19 offset:6144
	v_mul_f32_e32 v20, 0x3fb8aa3b, v20
	ds_write_b32 v26, v20 offset:8192
	v_cmp_gt_u32_e32 vcc, 16, v215
	s_and_saveexec_b64 s[100:101], vcc
	v_mul_f32_e32 v21, 0x3fb8aa3b, v21
	ds_write_b32 v27, v21 offset:10240
	s_or_b64 exec, exec, s[100:101]
	s_cmp_ge_i32 s45, s31
	s_cbranch_scc1 .LBB0_384
	s_mul_hi_u32 s54, s45, 0x60000
	s_mul_i32 s45, s45, 0x60000
	s_add_u32 s52, s43, s45
	s_addc_u32 s53, s44, s54
	s_add_i32 m0, s34, 0x4000
	v_lshl_add_u64 v[2:3], v[98:99], 1, s[52:53]
	s_add_u32 s52, s36, s45
	s_addc_u32 s53, s38, s54
	global_load_lds_dwordx4 v[2:3], off
	v_lshl_add_u64 v[2:3], v[0:1], 1, s[52:53]
	s_add_i32 m0, s34, 0x6000
	s_nop 0
	global_load_lds_dwordx4 v[2:3], off
